# GEMM unit scheduler: has_next as scalar compares instead of two 64-bit VALU compares (in/up unit heads)
# baseline (speedup 1.0000x reference)
.LBB0_203:
	s_add_i32 s96, s96, 1
	s_mul_i32 s9, s96, s97
	s_mul_hi_u32 s10, s96, s62
	s_add_i32 s10, s10, s9
	s_mul_i32 s9, s96, s62
	s_add_u32 s56, s9, s2
	s_addc_u32 s57, s10, s4
	s_cmp_eq_u32 s57, 0
	s_cselect_b32 s9, s56, -1
	s_cmp_lt_u32 s9, 0x3c0
	s_cselect_b64 s[38:39], exec, 0
	s_cbranch_scc0 .LBB0_205
	s_ashr_i32 s9, s56, 31
	s_lshr_b32 s9, s9, 29
	s_add_i32 s9, s56, s9
	s_ashr_i32 s10, s9, 3
	s_and_b32 s9, s9, -8
	s_sub_i32 s9, s56, s9
	s_cmp_lt_i32 s9, 0
	s_movk_i32 s11, 0x79
	s_cselect_b32 s11, s11, 0x78
	s_mul_i32 s9, s9, s11
	s_add_i32 s9, s9, s10
	s_mul_hi_i32 s10, s9, 0x88888889
	s_add_i32 s10, s10, s9
	s_lshr_b32 s11, s10, 31
	s_ashr_i32 s10, s10, 6
	s_add_i32 s10, s10, s11
	s_lshl_b32 s11, s10, 3
	s_mulk_i32 s10, 0x78
	s_sub_i32 s9, s9, s10
	s_ashr_i32 s52, s9, 3
	s_and_b32 s9, s9, 7
	s_add_i32 s54, s11, s9

.LBB0_1137:
	s_add_i32 s78, s78, 1
	s_mul_i32 s5, s78, s75
	s_mul_hi_u32 s6, s78, s56
	s_add_i32 s6, s6, s5
	s_mul_i32 s5, s78, s56
	s_add_u32 s50, s5, s2
	s_addc_u32 s51, s6, s59
	s_cmp_eq_u32 s51, 0
	s_cselect_b32 s5, s50, -1
	s_cmp_lt_u32 s5, 0x400
	s_cselect_b64 s[38:39], exec, 0
	s_cbranch_scc0 .LBB0_1143
	s_ashr_i32 s5, s50, 31
	s_lshr_b32 s5, s5, 29
	s_add_i32 s5, s50, s5
	s_and_b32 s6, s5, -8
	s_sub_i32 s6, s50, s6
	s_cmp_gt_i32 s6, -1
	s_mov_b64 s[46:47], -1
	s_cbranch_scc0 .LBB0_1140
	s_lshl_b32 s7, s6, 7
	s_mov_b64 s[46:47], 0
